# v70 + EpiMid part 2 hand-written (g/scale/shift vectors and rstd loaded once)
# speedup vs baseline: 1.0192x; 1.0123x over previous
; DI unsigned pk2(float lo, float hi) { unsigned r; asm("v_cvt_pk_bf16_f32 %0, %1, %2" : "=v"(r) : "v"(lo), "v"(hi)); return r; }
;     DI void operator()(f32x4 (&acc)[2][2][4][2], const pg8::Unit& u, int wr, int wc, int fr, int fq) const {
;     ...
;         asm volatile("s_waitcnt vmcnt(0) lgkmcnt(0)" ::: "memory"); __builtin_amdgcn_s_barrier(); asm volatile("" ::: "memory");
; #pragma unroll
;         for (int ai = 0; ai < 2; ++ai)
; #pragma unroll
;             for (int m = 0; m < 4; ++m) { const int rl = ai * 128 + wr * 64 + m * 16 + fr; const float rs = X[1024 + rl]; const size_t row = (size_t)u.pm * 256 + rl;
;                 const float* md = mod1 + (row >> 12) * 3072;
; #pragma unroll
;                 for (int bj = 0; bj < 2; ++bj)
; #pragma unroll
;                     for (int n = 0; n < 2; ++n) { const int col = col0 + bj * 128 + n * 16;
;                         const f32x4 gv = *(const f32x4*)(gno + col), sh = *(const f32x4*)(md + col), sc = *(const f32x4*)(md + 1024 + col);
;                         const f32x4 hv = acc[ai][bj][m][n] * rs * gv * (sc + 1.0f) + sh;
;                         u32x2 w; w.x = pk2(hv.x, hv.y); w.y = pk2(hv.z, hv.w); *(u32x2*)(H + row * DM + col) = w; }
;                 asm volatile("" ::: "memory"); }
.LBB0_808:
	s_or_b64 exec, exec, s[62:63]
	v_lshlrev_b64 v[172:173], 8, v[168:169]
	v_lshl_add_u64 v[176:177], v[172:173], 0, v[134:135]
	v_alignbit_b32 v166, v177, v176, 12
	v_mov_b64_e32 v[174:175], s[12:13]
	v_mad_u64_u32 v[170:171], s[10:11], v166, s94, v[174:175]
	v_lshrrev_b32_e32 v166, 12, v177
	v_mad_u32_u24 v171, v166, s94, v171
	v_lshl_add_u64 v[206:207], v[170:171], 0, s[48:49]
	v_lshlrev_b64 v[168:169], 2, v[158:159]
	s_waitcnt vmcnt(0) lgkmcnt(0)
	s_barrier
	v_lshl_add_u64 v[166:167], s[36:37], 0, v[168:169]
	v_lshl_add_u64 v[198:199], v[206:207], 0, v[168:169]
	v_lshl_add_u64 v[208:209], v[170:171], 0, v[168:169]
	global_load_dwordx4 v[130:133], v[166:167], off
	global_load_dwordx4 v[228:231], v[198:199], off
	global_load_dwordx4 v[178:181], v[208:209], off
	global_load_dwordx4 v[134:137], v[166:167], off offset:64
	global_load_dwordx4 v[232:235], v[198:199], off offset:64
	global_load_dwordx4 v[182:185], v[208:209], off offset:64
	global_load_dwordx4 v[138:141], v[166:167], off offset:512
	global_load_dwordx4 v[236:239], v[198:199], off offset:512
	global_load_dwordx4 v[186:189], v[208:209], off offset:512
	global_load_dwordx4 v[142:145], v[166:167], off offset:576
	global_load_dwordx4 v[240:243], v[198:199], off offset:576
	global_load_dwordx4 v[190:193], v[208:209], off offset:576
	v_and_b32_e32 v248, 15, v226
	v_lshrrev_b32_e32 v249, 8, v226
	v_lshl_or_b32 v248, v249, 6, v248
	v_lshl_add_u32 v248, v248, 2, s89
	ds_read_b32 v210, v248 offset:4096
	ds_read_b32 v212, v248 offset:4160
	ds_read_b32 v214, v248 offset:4224
	ds_read_b32 v216, v248 offset:4288
	ds_read_b32 v218, v248 offset:4608
	ds_read_b32 v220, v248 offset:4672
	ds_read_b32 v222, v248 offset:4736
	ds_read_b32 v224, v248 offset:4800
	v_lshlrev_b64 v[170:171], 1, v[158:159]
	v_lshlrev_b64 v[160:161], 11, v[176:177]
	v_lshl_add_u64 v[160:161], s[38:39], 0, v[160:161]
	v_lshl_add_u64 v[176:177], v[160:161], 0, v[170:171]
	s_mov_b32 s10, 0x8000
	s_mov_b32 s11, 0
	s_waitcnt vmcnt(0) lgkmcnt(0)
	v_pk_add_f32 v[228:229], v[228:229], 1.0 op_sel_hi:[1,0]
	v_pk_add_f32 v[230:231], v[230:231], 1.0 op_sel_hi:[1,0]
	v_pk_add_f32 v[232:233], v[232:233], 1.0 op_sel_hi:[1,0]
	v_pk_add_f32 v[234:235], v[234:235], 1.0 op_sel_hi:[1,0]
	v_pk_add_f32 v[236:237], v[236:237], 1.0 op_sel_hi:[1,0]
	v_pk_add_f32 v[238:239], v[238:239], 1.0 op_sel_hi:[1,0]
	v_pk_add_f32 v[240:241], v[240:241], 1.0 op_sel_hi:[1,0]
	v_pk_add_f32 v[242:243], v[242:243], 1.0 op_sel_hi:[1,0]
	v_pk_mul_f32 v[164:165], v[164:165], v[210:211] op_sel_hi:[1,0]
	v_pk_mul_f32 v[162:163], v[162:163], v[210:211] op_sel_hi:[1,0]
	v_pk_mul_f32 v[164:165], v[130:131], v[164:165]
	v_pk_mul_f32 v[162:163], v[132:133], v[162:163]
	v_pk_fma_f32 v[164:165], v[228:229], v[164:165], v[178:179]
	v_pk_fma_f32 v[162:163], v[230:231], v[162:163], v[180:181]
	v_cvt_pk_bf16_f32 v244, v164, v165
	v_cvt_pk_bf16_f32 v245, v162, v163
	global_store_dwordx2 v[176:177], v[244:245], off
	v_pk_mul_f32 v[126:127], v[126:127], v[210:211] op_sel_hi:[1,0]
	v_pk_mul_f32 v[122:123], v[122:123], v[210:211] op_sel_hi:[1,0]
	v_pk_mul_f32 v[126:127], v[134:135], v[126:127]
	v_pk_mul_f32 v[122:123], v[136:137], v[122:123]
	v_pk_fma_f32 v[126:127], v[232:233], v[126:127], v[182:183]
	v_pk_fma_f32 v[122:123], v[234:235], v[122:123], v[184:185]
	v_cvt_pk_bf16_f32 v246, v126, v127
	v_cvt_pk_bf16_f32 v247, v122, v123
	global_store_dwordx2 v[176:177], v[246:247], off offset:32
	v_pk_mul_f32 v[116:117], v[116:117], v[210:211] op_sel_hi:[1,0]
	v_pk_mul_f32 v[118:119], v[118:119], v[210:211] op_sel_hi:[1,0]
	v_pk_mul_f32 v[116:117], v[138:139], v[116:117]
	v_pk_mul_f32 v[118:119], v[140:141], v[118:119]
	v_pk_fma_f32 v[116:117], v[236:237], v[116:117], v[186:187]
	v_pk_fma_f32 v[118:119], v[238:239], v[118:119], v[188:189]
	v_cvt_pk_bf16_f32 v244, v116, v117
	v_cvt_pk_bf16_f32 v245, v118, v119
	global_store_dwordx2 v[176:177], v[244:245], off offset:256
	v_pk_mul_f32 v[112:113], v[112:113], v[210:211] op_sel_hi:[1,0]
	v_pk_mul_f32 v[114:115], v[114:115], v[210:211] op_sel_hi:[1,0]
	v_pk_mul_f32 v[112:113], v[142:143], v[112:113]
	v_pk_mul_f32 v[114:115], v[144:145], v[114:115]
	v_pk_fma_f32 v[112:113], v[240:241], v[112:113], v[190:191]
	v_pk_fma_f32 v[114:115], v[242:243], v[114:115], v[192:193]
	v_cvt_pk_bf16_f32 v246, v112, v113
	v_cvt_pk_bf16_f32 v247, v114, v115
	global_store_dwordx2 v[176:177], v[246:247], off offset:288
	v_lshl_add_u64 v[176:177], v[176:177], 0, s[10:11]
	v_pk_mul_f32 v[108:109], v[108:109], v[212:213] op_sel_hi:[1,0]
	v_pk_mul_f32 v[110:111], v[110:111], v[212:213] op_sel_hi:[1,0]
	v_pk_mul_f32 v[108:109], v[130:131], v[108:109]
	v_pk_mul_f32 v[110:111], v[132:133], v[110:111]
	v_pk_fma_f32 v[108:109], v[228:229], v[108:109], v[178:179]
	v_pk_fma_f32 v[110:111], v[230:231], v[110:111], v[180:181]
	v_cvt_pk_bf16_f32 v244, v108, v109
	v_cvt_pk_bf16_f32 v245, v110, v111
	global_store_dwordx2 v[176:177], v[244:245], off
	v_pk_mul_f32 v[104:105], v[104:105], v[212:213] op_sel_hi:[1,0]
	v_pk_mul_f32 v[106:107], v[106:107], v[212:213] op_sel_hi:[1,0]
	v_pk_mul_f32 v[104:105], v[134:135], v[104:105]
	v_pk_mul_f32 v[106:107], v[136:137], v[106:107]
	v_pk_fma_f32 v[104:105], v[232:233], v[104:105], v[182:183]
	v_pk_fma_f32 v[106:107], v[234:235], v[106:107], v[184:185]
	v_cvt_pk_bf16_f32 v246, v104, v105
	v_cvt_pk_bf16_f32 v247, v106, v107
	global_store_dwordx2 v[176:177], v[246:247], off offset:32
	v_pk_mul_f32 v[100:101], v[100:101], v[212:213] op_sel_hi:[1,0]
	v_pk_mul_f32 v[102:103], v[102:103], v[212:213] op_sel_hi:[1,0]
	v_pk_mul_f32 v[100:101], v[138:139], v[100:101]
	v_pk_mul_f32 v[102:103], v[140:141], v[102:103]
; DI unsigned pk2(float lo, float hi) { unsigned r; asm("v_cvt_pk_bf16_f32 %0, %1, %2" : "=v"(r) : "v"(lo), "v"(hi)); return r; }
;     DI void operator()(f32x4 (&acc)[2][2][4][2], const pg8::Unit& u, int wr, int wc, int fr, int fq) const {
;     ...
; #pragma unroll
;         for (int ai = 0; ai < 2; ++ai)
; #pragma unroll
;             for (int m = 0; m < 4; ++m) { const int rl = ai * 128 + wr * 64 + m * 16 + fr; const float rs = X[1024 + rl]; const size_t row = (size_t)u.pm * 256 + rl;
;                 const float* md = mod1 + (row >> 12) * 3072;
; #pragma unroll
;                 for (int bj = 0; bj < 2; ++bj)
; #pragma unroll
;                     for (int n = 0; n < 2; ++n) { const int col = col0 + bj * 128 + n * 16;
;                         const f32x4 gv = *(const f32x4*)(gno + col), sh = *(const f32x4*)(md + col), sc = *(const f32x4*)(md + 1024 + col);
;                         const f32x4 hv = acc[ai][bj][m][n] * rs * gv * (sc + 1.0f) + sh;
;                         u32x2 w; w.x = pk2(hv.x, hv.y); w.y = pk2(hv.z, hv.w); *(u32x2*)(H + row * DM + col) = w; }
;                 asm volatile("" ::: "memory"); }
	v_pk_fma_f32 v[100:101], v[236:237], v[100:101], v[186:187]
	v_pk_fma_f32 v[102:103], v[238:239], v[102:103], v[188:189]
	v_cvt_pk_bf16_f32 v244, v100, v101
	v_cvt_pk_bf16_f32 v245, v102, v103
	global_store_dwordx2 v[176:177], v[244:245], off offset:256
	v_pk_mul_f32 v[96:97], v[96:97], v[212:213] op_sel_hi:[1,0]
	v_pk_mul_f32 v[98:99], v[98:99], v[212:213] op_sel_hi:[1,0]
	v_pk_mul_f32 v[96:97], v[142:143], v[96:97]
	v_pk_mul_f32 v[98:99], v[144:145], v[98:99]
	v_pk_fma_f32 v[96:97], v[240:241], v[96:97], v[190:191]
	v_pk_fma_f32 v[98:99], v[242:243], v[98:99], v[192:193]
	v_cvt_pk_bf16_f32 v246, v96, v97
	v_cvt_pk_bf16_f32 v247, v98, v99
	global_store_dwordx2 v[176:177], v[246:247], off offset:288
	v_lshl_add_u64 v[176:177], v[176:177], 0, s[10:11]
	v_pk_mul_f32 v[92:93], v[92:93], v[214:215] op_sel_hi:[1,0]
	v_pk_mul_f32 v[94:95], v[94:95], v[214:215] op_sel_hi:[1,0]
	v_pk_mul_f32 v[92:93], v[130:131], v[92:93]
	v_pk_mul_f32 v[94:95], v[132:133], v[94:95]
	v_pk_fma_f32 v[92:93], v[228:229], v[92:93], v[178:179]
	v_pk_fma_f32 v[94:95], v[230:231], v[94:95], v[180:181]
	v_cvt_pk_bf16_f32 v244, v92, v93
	v_cvt_pk_bf16_f32 v245, v94, v95
	global_store_dwordx2 v[176:177], v[244:245], off
	v_pk_mul_f32 v[88:89], v[88:89], v[214:215] op_sel_hi:[1,0]
	v_pk_mul_f32 v[90:91], v[90:91], v[214:215] op_sel_hi:[1,0]
	v_pk_mul_f32 v[88:89], v[134:135], v[88:89]
	v_pk_mul_f32 v[90:91], v[136:137], v[90:91]
	v_pk_fma_f32 v[88:89], v[232:233], v[88:89], v[182:183]
	v_pk_fma_f32 v[90:91], v[234:235], v[90:91], v[184:185]
	v_cvt_pk_bf16_f32 v246, v88, v89
	v_cvt_pk_bf16_f32 v247, v90, v91
	global_store_dwordx2 v[176:177], v[246:247], off offset:32
	v_pk_mul_f32 v[84:85], v[84:85], v[214:215] op_sel_hi:[1,0]
	v_pk_mul_f32 v[86:87], v[86:87], v[214:215] op_sel_hi:[1,0]
	v_pk_mul_f32 v[84:85], v[138:139], v[84:85]
	v_pk_mul_f32 v[86:87], v[140:141], v[86:87]
	v_pk_fma_f32 v[84:85], v[236:237], v[84:85], v[186:187]
	v_pk_fma_f32 v[86:87], v[238:239], v[86:87], v[188:189]
	v_cvt_pk_bf16_f32 v244, v84, v85
	v_cvt_pk_bf16_f32 v245, v86, v87
	global_store_dwordx2 v[176:177], v[244:245], off offset:256
	v_pk_mul_f32 v[80:81], v[80:81], v[214:215] op_sel_hi:[1,0]
	v_pk_mul_f32 v[82:83], v[82:83], v[214:215] op_sel_hi:[1,0]
	v_pk_mul_f32 v[80:81], v[142:143], v[80:81]
	v_pk_mul_f32 v[82:83], v[144:145], v[82:83]
	v_pk_fma_f32 v[80:81], v[240:241], v[80:81], v[190:191]
	v_pk_fma_f32 v[82:83], v[242:243], v[82:83], v[192:193]
	v_cvt_pk_bf16_f32 v246, v80, v81
	v_cvt_pk_bf16_f32 v247, v82, v83
	global_store_dwordx2 v[176:177], v[246:247], off offset:288
	v_lshl_add_u64 v[176:177], v[176:177], 0, s[10:11]
	v_pk_mul_f32 v[76:77], v[76:77], v[216:217] op_sel_hi:[1,0]
	v_pk_mul_f32 v[78:79], v[78:79], v[216:217] op_sel_hi:[1,0]
	v_pk_mul_f32 v[76:77], v[130:131], v[76:77]
	v_pk_mul_f32 v[78:79], v[132:133], v[78:79]
	v_pk_fma_f32 v[76:77], v[228:229], v[76:77], v[178:179]
	v_pk_fma_f32 v[78:79], v[230:231], v[78:79], v[180:181]
	v_cvt_pk_bf16_f32 v244, v76, v77
	v_cvt_pk_bf16_f32 v245, v78, v79
	global_store_dwordx2 v[176:177], v[244:245], off
	v_pk_mul_f32 v[72:73], v[72:73], v[216:217] op_sel_hi:[1,0]
	v_pk_mul_f32 v[74:75], v[74:75], v[216:217] op_sel_hi:[1,0]
	v_pk_mul_f32 v[72:73], v[134:135], v[72:73]
	v_pk_mul_f32 v[74:75], v[136:137], v[74:75]
	v_pk_fma_f32 v[72:73], v[232:233], v[72:73], v[182:183]
	v_pk_fma_f32 v[74:75], v[234:235], v[74:75], v[184:185]
	v_cvt_pk_bf16_f32 v246, v72, v73
	v_cvt_pk_bf16_f32 v247, v74, v75
	global_store_dwordx2 v[176:177], v[246:247], off offset:32
	v_pk_mul_f32 v[68:69], v[68:69], v[216:217] op_sel_hi:[1,0]
	v_pk_mul_f32 v[70:71], v[70:71], v[216:217] op_sel_hi:[1,0]
	v_pk_mul_f32 v[68:69], v[138:139], v[68:69]
	v_pk_mul_f32 v[70:71], v[140:141], v[70:71]
	v_pk_fma_f32 v[68:69], v[236:237], v[68:69], v[186:187]
	v_pk_fma_f32 v[70:71], v[238:239], v[70:71], v[188:189]
	v_cvt_pk_bf16_f32 v244, v68, v69
	v_cvt_pk_bf16_f32 v245, v70, v71
	global_store_dwordx2 v[176:177], v[244:245], off offset:256
	v_pk_mul_f32 v[64:65], v[64:65], v[216:217] op_sel_hi:[1,0]
	v_pk_mul_f32 v[66:67], v[66:67], v[216:217] op_sel_hi:[1,0]
	v_pk_mul_f32 v[64:65], v[142:143], v[64:65]
	v_pk_mul_f32 v[66:67], v[144:145], v[66:67]
	v_pk_fma_f32 v[64:65], v[240:241], v[64:65], v[190:191]
	v_pk_fma_f32 v[66:67], v[242:243], v[66:67], v[192:193]
	v_cvt_pk_bf16_f32 v246, v64, v65
	v_cvt_pk_bf16_f32 v247, v66, v67
	global_store_dwordx2 v[176:177], v[246:247], off offset:288
	s_mov_b32 s10, 0x28000
	v_lshl_add_u64 v[176:177], v[176:177], 0, s[10:11]
	s_mov_b32 s10, 0x8000
	v_pk_mul_f32 v[60:61], v[60:61], v[218:219] op_sel_hi:[1,0]
	v_pk_mul_f32 v[62:63], v[62:63], v[218:219] op_sel_hi:[1,0]
	v_pk_mul_f32 v[60:61], v[130:131], v[60:61]
	v_pk_mul_f32 v[62:63], v[132:133], v[62:63]
	v_pk_fma_f32 v[60:61], v[228:229], v[60:61], v[178:179]
	v_pk_fma_f32 v[62:63], v[230:231], v[62:63], v[180:181]
	v_cvt_pk_bf16_f32 v244, v60, v61
	v_cvt_pk_bf16_f32 v245, v62, v63
	global_store_dwordx2 v[176:177], v[244:245], off
	v_pk_mul_f32 v[56:57], v[56:57], v[218:219] op_sel_hi:[1,0]
	v_pk_mul_f32 v[58:59], v[58:59], v[218:219] op_sel_hi:[1,0]
	v_pk_mul_f32 v[56:57], v[134:135], v[56:57]
	v_pk_mul_f32 v[58:59], v[136:137], v[58:59]
	v_pk_fma_f32 v[56:57], v[232:233], v[56:57], v[182:183]
	v_pk_fma_f32 v[58:59], v[234:235], v[58:59], v[184:185]
	v_cvt_pk_bf16_f32 v246, v56, v57
	v_cvt_pk_bf16_f32 v247, v58, v59
	global_store_dwordx2 v[176:177], v[246:247], off offset:32
	v_pk_mul_f32 v[52:53], v[52:53], v[218:219] op_sel_hi:[1,0]
	v_pk_mul_f32 v[54:55], v[54:55], v[218:219] op_sel_hi:[1,0]
	v_pk_mul_f32 v[52:53], v[138:139], v[52:53]
	v_pk_mul_f32 v[54:55], v[140:141], v[54:55]
; DI unsigned pk2(float lo, float hi) { unsigned r; asm("v_cvt_pk_bf16_f32 %0, %1, %2" : "=v"(r) : "v"(lo), "v"(hi)); return r; }
;     DI void operator()(f32x4 (&acc)[2][2][4][2], const pg8::Unit& u, int wr, int wc, int fr, int fq) const {
;     ...
; #pragma unroll
;         for (int ai = 0; ai < 2; ++ai)
; #pragma unroll
;             for (int m = 0; m < 4; ++m) { const int rl = ai * 128 + wr * 64 + m * 16 + fr; const float rs = X[1024 + rl]; const size_t row = (size_t)u.pm * 256 + rl;
;                 const float* md = mod1 + (row >> 12) * 3072;
; #pragma unroll
;                 for (int bj = 0; bj < 2; ++bj)
; #pragma unroll
;                     for (int n = 0; n < 2; ++n) { const int col = col0 + bj * 128 + n * 16;
;                         const f32x4 gv = *(const f32x4*)(gno + col), sh = *(const f32x4*)(md + col), sc = *(const f32x4*)(md + 1024 + col);
;                         const f32x4 hv = acc[ai][bj][m][n] * rs * gv * (sc + 1.0f) + sh;
;                         u32x2 w; w.x = pk2(hv.x, hv.y); w.y = pk2(hv.z, hv.w); *(u32x2*)(H + row * DM + col) = w; }
;                 asm volatile("" ::: "memory"); }
	v_pk_fma_f32 v[52:53], v[236:237], v[52:53], v[186:187]
	v_pk_fma_f32 v[54:55], v[238:239], v[54:55], v[188:189]
	v_cvt_pk_bf16_f32 v244, v52, v53
	v_cvt_pk_bf16_f32 v245, v54, v55
	global_store_dwordx2 v[176:177], v[244:245], off offset:256
	v_pk_mul_f32 v[48:49], v[48:49], v[218:219] op_sel_hi:[1,0]
	v_pk_mul_f32 v[50:51], v[50:51], v[218:219] op_sel_hi:[1,0]
	v_pk_mul_f32 v[48:49], v[142:143], v[48:49]
	v_pk_mul_f32 v[50:51], v[144:145], v[50:51]
	v_pk_fma_f32 v[48:49], v[240:241], v[48:49], v[190:191]
	v_pk_fma_f32 v[50:51], v[242:243], v[50:51], v[192:193]
	v_cvt_pk_bf16_f32 v246, v48, v49
	v_cvt_pk_bf16_f32 v247, v50, v51
	global_store_dwordx2 v[176:177], v[246:247], off offset:288
	v_lshl_add_u64 v[176:177], v[176:177], 0, s[10:11]
	v_pk_mul_f32 v[44:45], v[44:45], v[220:221] op_sel_hi:[1,0]
	v_pk_mul_f32 v[46:47], v[46:47], v[220:221] op_sel_hi:[1,0]
	v_pk_mul_f32 v[44:45], v[130:131], v[44:45]
	v_pk_mul_f32 v[46:47], v[132:133], v[46:47]
	v_pk_fma_f32 v[44:45], v[228:229], v[44:45], v[178:179]
	v_pk_fma_f32 v[46:47], v[230:231], v[46:47], v[180:181]
	v_cvt_pk_bf16_f32 v244, v44, v45
	v_cvt_pk_bf16_f32 v245, v46, v47
	global_store_dwordx2 v[176:177], v[244:245], off
	v_pk_mul_f32 v[40:41], v[40:41], v[220:221] op_sel_hi:[1,0]
	v_pk_mul_f32 v[42:43], v[42:43], v[220:221] op_sel_hi:[1,0]
	v_pk_mul_f32 v[40:41], v[134:135], v[40:41]
	v_pk_mul_f32 v[42:43], v[136:137], v[42:43]
	v_pk_fma_f32 v[40:41], v[232:233], v[40:41], v[182:183]
	v_pk_fma_f32 v[42:43], v[234:235], v[42:43], v[184:185]
	v_cvt_pk_bf16_f32 v246, v40, v41
	v_cvt_pk_bf16_f32 v247, v42, v43
	global_store_dwordx2 v[176:177], v[246:247], off offset:32
	v_pk_mul_f32 v[36:37], v[36:37], v[220:221] op_sel_hi:[1,0]
	v_pk_mul_f32 v[38:39], v[38:39], v[220:221] op_sel_hi:[1,0]
	v_pk_mul_f32 v[36:37], v[138:139], v[36:37]
	v_pk_mul_f32 v[38:39], v[140:141], v[38:39]
	v_pk_fma_f32 v[36:37], v[236:237], v[36:37], v[186:187]
	v_pk_fma_f32 v[38:39], v[238:239], v[38:39], v[188:189]
	v_cvt_pk_bf16_f32 v244, v36, v37
	v_cvt_pk_bf16_f32 v245, v38, v39
	global_store_dwordx2 v[176:177], v[244:245], off offset:256
	v_pk_mul_f32 v[32:33], v[32:33], v[220:221] op_sel_hi:[1,0]
	v_pk_mul_f32 v[34:35], v[34:35], v[220:221] op_sel_hi:[1,0]
	v_pk_mul_f32 v[32:33], v[142:143], v[32:33]
	v_pk_mul_f32 v[34:35], v[144:145], v[34:35]
	v_pk_fma_f32 v[32:33], v[240:241], v[32:33], v[190:191]
	v_pk_fma_f32 v[34:35], v[242:243], v[34:35], v[192:193]
	v_cvt_pk_bf16_f32 v246, v32, v33
	v_cvt_pk_bf16_f32 v247, v34, v35
	global_store_dwordx2 v[176:177], v[246:247], off offset:288
	v_lshl_add_u64 v[176:177], v[176:177], 0, s[10:11]
	v_pk_mul_f32 v[28:29], v[28:29], v[222:223] op_sel_hi:[1,0]
	v_pk_mul_f32 v[30:31], v[30:31], v[222:223] op_sel_hi:[1,0]
	v_pk_mul_f32 v[28:29], v[130:131], v[28:29]
	v_pk_mul_f32 v[30:31], v[132:133], v[30:31]
	v_pk_fma_f32 v[28:29], v[228:229], v[28:29], v[178:179]
	v_pk_fma_f32 v[30:31], v[230:231], v[30:31], v[180:181]
	v_cvt_pk_bf16_f32 v244, v28, v29
	v_cvt_pk_bf16_f32 v245, v30, v31
	global_store_dwordx2 v[176:177], v[244:245], off
	v_pk_mul_f32 v[24:25], v[24:25], v[222:223] op_sel_hi:[1,0]
	v_pk_mul_f32 v[26:27], v[26:27], v[222:223] op_sel_hi:[1,0]
	v_pk_mul_f32 v[24:25], v[134:135], v[24:25]
	v_pk_mul_f32 v[26:27], v[136:137], v[26:27]
	v_pk_fma_f32 v[24:25], v[232:233], v[24:25], v[182:183]
	v_pk_fma_f32 v[26:27], v[234:235], v[26:27], v[184:185]
	v_cvt_pk_bf16_f32 v246, v24, v25
	v_cvt_pk_bf16_f32 v247, v26, v27
	global_store_dwordx2 v[176:177], v[246:247], off offset:32
	v_pk_mul_f32 v[20:21], v[20:21], v[222:223] op_sel_hi:[1,0]
	v_pk_mul_f32 v[22:23], v[22:23], v[222:223] op_sel_hi:[1,0]
	v_pk_mul_f32 v[20:21], v[138:139], v[20:21]
	v_pk_mul_f32 v[22:23], v[140:141], v[22:23]
	v_pk_fma_f32 v[20:21], v[236:237], v[20:21], v[186:187]
	v_pk_fma_f32 v[22:23], v[238:239], v[22:23], v[188:189]
	v_cvt_pk_bf16_f32 v244, v20, v21
	v_cvt_pk_bf16_f32 v245, v22, v23
	global_store_dwordx2 v[176:177], v[244:245], off offset:256
	v_pk_mul_f32 v[16:17], v[16:17], v[222:223] op_sel_hi:[1,0]
	v_pk_mul_f32 v[18:19], v[18:19], v[222:223] op_sel_hi:[1,0]
	v_pk_mul_f32 v[16:17], v[142:143], v[16:17]
	v_pk_mul_f32 v[18:19], v[144:145], v[18:19]
	v_pk_fma_f32 v[16:17], v[240:241], v[16:17], v[190:191]
	v_pk_fma_f32 v[18:19], v[242:243], v[18:19], v[192:193]
	v_cvt_pk_bf16_f32 v246, v16, v17
	v_cvt_pk_bf16_f32 v247, v18, v19
	global_store_dwordx2 v[176:177], v[246:247], off offset:288
	v_lshl_add_u64 v[176:177], v[176:177], 0, s[10:11]
	v_pk_mul_f32 v[12:13], v[12:13], v[224:225] op_sel_hi:[1,0]
	v_pk_mul_f32 v[14:15], v[14:15], v[224:225] op_sel_hi:[1,0]
	v_pk_mul_f32 v[12:13], v[130:131], v[12:13]
	v_pk_mul_f32 v[14:15], v[132:133], v[14:15]
	v_pk_fma_f32 v[12:13], v[228:229], v[12:13], v[178:179]
	v_pk_fma_f32 v[14:15], v[230:231], v[14:15], v[180:181]
	v_cvt_pk_bf16_f32 v244, v12, v13
	v_cvt_pk_bf16_f32 v245, v14, v15
	global_store_dwordx2 v[176:177], v[244:245], off
	v_pk_mul_f32 v[8:9], v[8:9], v[224:225] op_sel_hi:[1,0]
	v_pk_mul_f32 v[10:11], v[10:11], v[224:225] op_sel_hi:[1,0]
	v_pk_mul_f32 v[8:9], v[134:135], v[8:9]
	v_pk_mul_f32 v[10:11], v[136:137], v[10:11]
	v_pk_fma_f32 v[8:9], v[232:233], v[8:9], v[182:183]
	v_pk_fma_f32 v[10:11], v[234:235], v[10:11], v[184:185]
	v_cvt_pk_bf16_f32 v246, v8, v9
	v_cvt_pk_bf16_f32 v247, v10, v11
	global_store_dwordx2 v[176:177], v[246:247], off offset:32
	v_pk_mul_f32 v[4:5], v[4:5], v[224:225] op_sel_hi:[1,0]
	v_pk_mul_f32 v[6:7], v[6:7], v[224:225] op_sel_hi:[1,0]
	v_pk_mul_f32 v[4:5], v[138:139], v[4:5]
	v_pk_mul_f32 v[6:7], v[140:141], v[6:7]
	v_pk_fma_f32 v[4:5], v[236:237], v[4:5], v[186:187]
	v_pk_fma_f32 v[6:7], v[238:239], v[6:7], v[188:189]
	v_cvt_pk_bf16_f32 v244, v4, v5
	v_cvt_pk_bf16_f32 v245, v6, v7
	global_store_dwordx2 v[176:177], v[244:245], off offset:256
	v_pk_mul_f32 v[0:1], v[0:1], v[224:225] op_sel_hi:[1,0]
	v_pk_mul_f32 v[2:3], v[2:3], v[224:225] op_sel_hi:[1,0]
	v_pk_mul_f32 v[0:1], v[142:143], v[0:1]
	v_pk_mul_f32 v[2:3], v[144:145], v[2:3]
	v_pk_fma_f32 v[0:1], v[240:241], v[0:1], v[190:191]
	v_pk_fma_f32 v[2:3], v[242:243], v[2:3], v[192:193]
	v_cvt_pk_bf16_f32 v246, v0, v1
	v_cvt_pk_bf16_f32 v247, v2, v3
	global_store_dwordx2 v[176:177], v[246:247], off offset:288
	s_andn2_b64 vcc, exec, s[8:9]
	s_mov_b64 s[8:9], -1
	s_waitcnt lgkmcnt(0)
	s_barrier
	s_cbranch_vccnz .LBB0_765
	s_andn2_b64 vcc, exec, s[16:17]
	s_cbranch_vccnz .LBB0_764
	s_barrier
	s_branch .LBB0_764

; template <class F>
; DI void small_gemm(LAS unsigned char* lds, const bf16_t* A, int lda, const bf16_t* Wt, int ldb, int K, int N, int tile0, int tstride, F f) {
;     ...
;         const bf16_t* ap = A + (size_t)r * lda + wid * kw + 8 * h;
;         const bf16_t* bp = Wt + (size_t)(n0 + r) * ldb + wid * kw + 8 * h;
; #pragma unroll 8
;         for (int ks = 0; ks < kw; ks += 16) {
;             const bf16x8 a = *(const bf16x8*)(ap + ks), b = *(const bf16x8*)(bp + ks);
;             acc = __builtin_amdgcn_mfma_f32_32x32x16_bf16(a, b, acc, 0, 0, 0);
;         }
; #pragma unroll
;         for (int i = 0; i < 16; ++i) red[wid * 1024 + i * 64 + lane] = acc[i];
;         __syncthreads();
.LBB0_816:
	global_load_dwordx4 v[32:35], v[28:29], off offset:-128
	global_load_dwordx4 v[36:39], v[26:27], off offset:-128
	global_load_dwordx4 v[40:43], v[28:29], off offset:-96
	global_load_dwordx4 v[44:47], v[26:27], off offset:-96
	global_load_dwordx4 v[48:51], v[28:29], off offset:-64
	global_load_dwordx4 v[52:55], v[26:27], off offset:-64
	global_load_dwordx4 v[56:59], v[28:29], off offset:-32
	global_load_dwordx4 v[60:63], v[26:27], off offset:-32
	global_load_dwordx4 v[64:67], v[28:29], off
	global_load_dwordx4 v[68:71], v[26:27], off
	global_load_dwordx4 v[72:75], v[28:29], off offset:32
	global_load_dwordx4 v[76:79], v[26:27], off offset:32
	global_load_dwordx4 v[80:83], v[28:29], off offset:64
	global_load_dwordx4 v[84:87], v[26:27], off offset:64
	global_load_dwordx4 v[88:91], v[28:29], off offset:96
	global_load_dwordx4 v[92:95], v[26:27], off offset:96
	global_load_dwordx4 v[96:99], v[28:29], off offset:128
	global_load_dwordx4 v[100:103], v[26:27], off offset:128
	global_load_dwordx4 v[104:107], v[28:29], off offset:160
	global_load_dwordx4 v[108:111], v[26:27], off offset:160
	global_load_dwordx4 v[112:115], v[28:29], off offset:192
	global_load_dwordx4 v[116:119], v[26:27], off offset:192
	global_load_dwordx4 v[120:123], v[28:29], off offset:224
	global_load_dwordx4 v[124:127], v[26:27], off offset:224
	global_load_dwordx4 v[132:135], v[28:29], off offset:256
	global_load_dwordx4 v[136:139], v[26:27], off offset:256
	global_load_dwordx4 v[140:143], v[28:29], off offset:288
	global_load_dwordx4 v[144:147], v[26:27], off offset:288
	global_load_dwordx4 v[148:151], v[28:29], off offset:320
	global_load_dwordx4 v[152:155], v[26:27], off offset:320
	global_load_dwordx4 v[156:159], v[28:29], off offset:352
	global_load_dwordx4 v[160:163], v[26:27], off offset:352
	s_waitcnt vmcnt(30)
	v_mfma_f32_32x32x16_bf16 v[0:15], v[32:35], v[36:39], v[0:15]
	s_waitcnt vmcnt(28)
	v_mfma_f32_32x32x16_bf16 v[0:15], v[40:43], v[44:47], v[0:15]
	s_waitcnt vmcnt(26)
	v_mfma_f32_32x32x16_bf16 v[0:15], v[48:51], v[52:55], v[0:15]
	s_waitcnt vmcnt(24)
	v_mfma_f32_32x32x16_bf16 v[0:15], v[56:59], v[60:63], v[0:15]
	s_waitcnt vmcnt(22)
	v_mfma_f32_32x32x16_bf16 v[0:15], v[64:67], v[68:71], v[0:15]
	s_waitcnt vmcnt(20)
	v_mfma_f32_32x32x16_bf16 v[0:15], v[72:75], v[76:79], v[0:15]
	s_waitcnt vmcnt(18)
	v_mfma_f32_32x32x16_bf16 v[0:15], v[80:83], v[84:87], v[0:15]
	s_waitcnt vmcnt(16)
	v_mfma_f32_32x32x16_bf16 v[0:15], v[88:91], v[92:95], v[0:15]
	s_waitcnt vmcnt(14)
	v_mfma_f32_32x32x16_bf16 v[0:15], v[96:99], v[100:103], v[0:15]
	s_waitcnt vmcnt(12)
	v_mfma_f32_32x32x16_bf16 v[0:15], v[104:107], v[108:111], v[0:15]
	s_waitcnt vmcnt(10)
	v_mfma_f32_32x32x16_bf16 v[0:15], v[112:115], v[116:119], v[0:15]
	s_waitcnt vmcnt(8)
	v_mfma_f32_32x32x16_bf16 v[0:15], v[120:123], v[124:127], v[0:15]
	s_waitcnt vmcnt(6)
	v_mfma_f32_32x32x16_bf16 v[0:15], v[132:135], v[136:139], v[0:15]
	s_waitcnt vmcnt(4)
	v_mfma_f32_32x32x16_bf16 v[0:15], v[140:143], v[144:147], v[0:15]
	s_waitcnt vmcnt(2)
	v_mfma_f32_32x32x16_bf16 v[0:15], v[148:151], v[152:155], v[0:15]
	s_waitcnt vmcnt(0)
	v_mfma_f32_32x32x16_bf16 v[0:15], v[156:159], v[160:163], v[0:15]
	s_nop 10
	ds_write2st64_b32 v31, v0, v1 offset1:1
	ds_write2st64_b32 v31, v2, v3 offset0:2 offset1:3
	ds_write2st64_b32 v31, v4, v5 offset0:4 offset1:5
	ds_write2st64_b32 v31, v6, v7 offset0:6 offset1:7
	ds_write2st64_b32 v31, v8, v9 offset0:8 offset1:9
	ds_write2st64_b32 v31, v10, v11 offset0:10 offset1:11
	ds_write2st64_b32 v31, v12, v13 offset0:12 offset1:13
	ds_write2st64_b32 v31, v14, v15 offset0:14 offset1:15
	s_waitcnt lgkmcnt(0)
	s_barrier
	s_and_saveexec_b64 s[10:11], s[6:7]
	s_cbranch_execz .LBB0_814
	v_lshl_or_b32 v0, s40, 5, v30
	v_ashrrev_i32_e32 v1, 31, v0
	v_lshl_add_u64 v[2:3], v[0:1], 1, s[0:1]
	s_mov_b64 s[14:15], 0
	v_mov_b32_e32 v4, v22
	v_mov_b32_e32 v5, v17

; template <class F>
; DI void small_gemm(LAS unsigned char* lds, const bf16_t* A, int lda, const bf16_t* Wt, int ldb, int K, int N, int tile0, int tstride, F f) {
;     ...
;         const bf16_t* ap = A + (size_t)r * lda + wid * kw + 8 * h;
;         const bf16_t* bp = Wt + (size_t)(n0 + r) * ldb + wid * kw + 8 * h;
; #pragma unroll 8
;         for (int ks = 0; ks < kw; ks += 16) {
;             const bf16x8 a = *(const bf16x8*)(ap + ks), b = *(const bf16x8*)(bp + ks);
;             acc = __builtin_amdgcn_mfma_f32_32x32x16_bf16(a, b, acc, 0, 0, 0);
;         }
; #pragma unroll
;         for (int i = 0; i < 16; ++i) red[wid * 1024 + i * 64 + lane] = acc[i];
;         __syncthreads();
.LBB0_2242:
	global_load_dwordx4 v[32:35], v[28:29], off offset:-128
	global_load_dwordx4 v[36:39], v[26:27], off offset:-128
	global_load_dwordx4 v[40:43], v[28:29], off offset:-96
	global_load_dwordx4 v[44:47], v[26:27], off offset:-96
	global_load_dwordx4 v[48:51], v[28:29], off offset:-64
	global_load_dwordx4 v[52:55], v[26:27], off offset:-64
	global_load_dwordx4 v[56:59], v[28:29], off offset:-32
	global_load_dwordx4 v[60:63], v[26:27], off offset:-32
	global_load_dwordx4 v[64:67], v[28:29], off
	global_load_dwordx4 v[68:71], v[26:27], off
	global_load_dwordx4 v[72:75], v[28:29], off offset:32
	global_load_dwordx4 v[76:79], v[26:27], off offset:32
	global_load_dwordx4 v[80:83], v[28:29], off offset:64
	global_load_dwordx4 v[84:87], v[26:27], off offset:64
	global_load_dwordx4 v[88:91], v[28:29], off offset:96
	global_load_dwordx4 v[92:95], v[26:27], off offset:96
	global_load_dwordx4 v[96:99], v[28:29], off offset:128
	global_load_dwordx4 v[100:103], v[26:27], off offset:128
	global_load_dwordx4 v[104:107], v[28:29], off offset:160
	global_load_dwordx4 v[108:111], v[26:27], off offset:160
	global_load_dwordx4 v[112:115], v[28:29], off offset:192
	global_load_dwordx4 v[116:119], v[26:27], off offset:192
	global_load_dwordx4 v[120:123], v[28:29], off offset:224
	global_load_dwordx4 v[124:127], v[26:27], off offset:224
	global_load_dwordx4 v[132:135], v[28:29], off offset:256
	global_load_dwordx4 v[136:139], v[26:27], off offset:256
	global_load_dwordx4 v[140:143], v[28:29], off offset:288
	global_load_dwordx4 v[144:147], v[26:27], off offset:288
	global_load_dwordx4 v[148:151], v[28:29], off offset:320
	global_load_dwordx4 v[152:155], v[26:27], off offset:320
	global_load_dwordx4 v[156:159], v[28:29], off offset:352
	global_load_dwordx4 v[160:163], v[26:27], off offset:352
	s_waitcnt vmcnt(30)
	v_mfma_f32_32x32x16_bf16 v[0:15], v[32:35], v[36:39], v[0:15]
	s_waitcnt vmcnt(28)
	v_mfma_f32_32x32x16_bf16 v[0:15], v[40:43], v[44:47], v[0:15]
	s_waitcnt vmcnt(26)
	v_mfma_f32_32x32x16_bf16 v[0:15], v[48:51], v[52:55], v[0:15]
	s_waitcnt vmcnt(24)
	v_mfma_f32_32x32x16_bf16 v[0:15], v[56:59], v[60:63], v[0:15]
	s_waitcnt vmcnt(22)
	v_mfma_f32_32x32x16_bf16 v[0:15], v[64:67], v[68:71], v[0:15]
	s_waitcnt vmcnt(20)
	v_mfma_f32_32x32x16_bf16 v[0:15], v[72:75], v[76:79], v[0:15]
	s_waitcnt vmcnt(18)
	v_mfma_f32_32x32x16_bf16 v[0:15], v[80:83], v[84:87], v[0:15]
	s_waitcnt vmcnt(16)
	v_mfma_f32_32x32x16_bf16 v[0:15], v[88:91], v[92:95], v[0:15]
	s_waitcnt vmcnt(14)
	v_mfma_f32_32x32x16_bf16 v[0:15], v[96:99], v[100:103], v[0:15]
	s_waitcnt vmcnt(12)
	v_mfma_f32_32x32x16_bf16 v[0:15], v[104:107], v[108:111], v[0:15]
	s_waitcnt vmcnt(10)
	v_mfma_f32_32x32x16_bf16 v[0:15], v[112:115], v[116:119], v[0:15]
	s_waitcnt vmcnt(8)
	v_mfma_f32_32x32x16_bf16 v[0:15], v[120:123], v[124:127], v[0:15]
	s_waitcnt vmcnt(6)
	v_mfma_f32_32x32x16_bf16 v[0:15], v[132:135], v[136:139], v[0:15]
	s_waitcnt vmcnt(4)
	v_mfma_f32_32x32x16_bf16 v[0:15], v[140:143], v[144:147], v[0:15]
	s_waitcnt vmcnt(2)
	v_mfma_f32_32x32x16_bf16 v[0:15], v[148:151], v[152:155], v[0:15]
	s_waitcnt vmcnt(0)
	v_mfma_f32_32x32x16_bf16 v[0:15], v[156:159], v[160:163], v[0:15]
	s_nop 10
	ds_write2st64_b32 v30, v0, v1 offset1:1
	ds_write2st64_b32 v30, v2, v3 offset0:2 offset1:3
	ds_write2st64_b32 v30, v4, v5 offset0:4 offset1:5
	ds_write2st64_b32 v30, v6, v7 offset0:6 offset1:7
	ds_write2st64_b32 v30, v8, v9 offset0:8 offset1:9
	ds_write2st64_b32 v30, v10, v11 offset0:10 offset1:11
	ds_write2st64_b32 v30, v12, v13 offset0:12 offset1:13
	ds_write2st64_b32 v30, v14, v15 offset0:14 offset1:15
	s_waitcnt lgkmcnt(0)
	s_barrier
	s_and_saveexec_b64 s[8:9], s[0:1]
	s_cbranch_execz .LBB0_2240
	v_lshl_or_b32 v0, s16, 5, v17
	v_ashrrev_i32_e32 v1, 31, v0
	s_mov_b64 s[12:13], 0
	v_mov_b32_e32 v2, v22
	v_mov_b32_e32 v3, v226
